# matrix segment of the pipelined attention loops runs at raised wave priority (s_setprio 3 after the rendezvous, back to 0 at the next softmax segment)
# speedup vs baseline: 1.0495x; 1.0017x over previous
;     ...
;         kv_loop<128, true>(lds, Kb, VTb, 4096, ntl, 0, [](int j) { return j + 1; }, [&](int j, const unsigned char* sb) {
;             const int k0 = j * 64;
;             if (k0 <= wq0 + 31) {
;                 f32x16 s0, s1; attn_scores(sb, qf, r, h, s0, s1);
;                 if (k0 + 63 > wq0) {
.Ldl_loop:
	s_setprio 0
	s_lshl_b32 s64, s24, 6
	s_cmp_le_i32 s64, s60
	s_cbranch_scc0 .Ldl_xdone
	s_add_i32 s65, s64, 63
	s_cmp_gt_i32 s65, s59
	s_cbranch_scc0 .Ldl_nomask
	v_mov_b32_e32 v2, s64

; DI int crow(int i, int h) { return (i & 3) + 8 * (i >> 2) + 4 * h; }
; #define NEG_INF (-__builtin_inff())
;     ...
;                 if (k0 + 63 > wq0) {
; #pragma unroll
;                     for (int i = 0; i < 16; ++i) {
;                         const int kl = k0 + crow(i, h);
;                         if (kl > qpos) s0[i] = NEG_INF;
;                         if (kl + 32 > qpos) s1[i] = NEG_INF;
;                     }
;                 }
	v_or_b32_e32 v2, v2, v192
	v_or_b32_e32 v7, 32, v2
	v_cmp_le_i32_e32 vcc, v7, v162
	v_or_b32_e32 v7, 33, v2
	s_nop 5
	v_cndmask_b32_e32 v98, v184, v98, vcc
	v_cmp_lt_i32_e32 vcc, v2, v162
	s_nop 1
	v_cndmask_b32_e32 v115, v184, v115, vcc
	v_cmp_le_i32_e32 vcc, v2, v162
	s_nop 1
	v_cndmask_b32_e32 v114, v184, v114, vcc
	v_cmp_le_i32_e32 vcc, v7, v162
	v_or_b32_e32 v7, 2, v2
	s_nop 0
	v_cndmask_b32_e32 v99, v184, v99, vcc
	v_cmp_le_i32_e32 vcc, v7, v162
	v_or_b32_e32 v7, 34, v2
	s_nop 0
	v_cndmask_b32_e32 v116, v184, v116, vcc
	v_cmp_le_i32_e32 vcc, v7, v162
	v_or_b32_e32 v7, 3, v2
	s_nop 0
	v_cndmask_b32_e32 v100, v184, v100, vcc
	v_cmp_le_i32_e32 vcc, v7, v162
	v_or_b32_e32 v7, 35, v2
	s_nop 0
	v_cndmask_b32_e32 v117, v184, v117, vcc
	v_cmp_le_i32_e32 vcc, v7, v162
	v_or_b32_e32 v7, 8, v2
	s_nop 0
	v_cndmask_b32_e32 v101, v184, v101, vcc
	v_cmp_le_i32_e32 vcc, v7, v162
	v_or_b32_e32 v7, 40, v2
	s_nop 0
	v_cndmask_b32_e32 v118, v184, v118, vcc
	v_cmp_le_i32_e32 vcc, v7, v162
	v_or_b32_e32 v7, 9, v2
	s_nop 0
	v_cndmask_b32_e32 v102, v184, v102, vcc
	v_cmp_le_i32_e32 vcc, v7, v162
	v_or_b32_e32 v7, 41, v2
	s_nop 0
	v_cndmask_b32_e32 v119, v184, v119, vcc
	v_cmp_le_i32_e32 vcc, v7, v162
	v_or_b32_e32 v7, 10, v2
	s_nop 0
	v_cndmask_b32_e32 v103, v184, v103, vcc
	v_cmp_le_i32_e32 vcc, v7, v162
	v_or_b32_e32 v7, 42, v2
	s_nop 0
	v_cndmask_b32_e32 v120, v184, v120, vcc
	v_cmp_le_i32_e32 vcc, v7, v162
	v_or_b32_e32 v7, 11, v2
	s_nop 0
	v_cndmask_b32_e32 v104, v184, v104, vcc
	v_cmp_le_i32_e32 vcc, v7, v162
	v_or_b32_e32 v7, 43, v2
	s_nop 0
	v_cndmask_b32_e32 v121, v184, v121, vcc
	v_cmp_le_i32_e32 vcc, v7, v162
	v_or_b32_e32 v7, 16, v2
	s_nop 0
	v_cndmask_b32_e32 v105, v184, v105, vcc
	v_cmp_le_i32_e32 vcc, v7, v162
	v_or_b32_e32 v7, 48, v2
	s_nop 0
	v_cndmask_b32_e32 v122, v184, v122, vcc
	v_cmp_le_i32_e32 vcc, v7, v162
	v_or_b32_e32 v7, 17, v2
	s_nop 0
	v_cndmask_b32_e32 v106, v184, v106, vcc
	v_cmp_le_i32_e32 vcc, v7, v162
	v_or_b32_e32 v7, 49, v2
	s_nop 0
	v_cndmask_b32_e32 v123, v184, v123, vcc
	v_cmp_le_i32_e32 vcc, v7, v162
	v_or_b32_e32 v7, 18, v2
	s_nop 0
	v_cndmask_b32_e32 v107, v184, v107, vcc
	v_cmp_le_i32_e32 vcc, v7, v162
	v_or_b32_e32 v7, 50, v2
	s_nop 0
	v_cndmask_b32_e32 v124, v184, v124, vcc
	v_cmp_le_i32_e32 vcc, v7, v162
	v_or_b32_e32 v7, 19, v2
	s_nop 0
	v_cndmask_b32_e32 v108, v184, v108, vcc
	v_cmp_le_i32_e32 vcc, v7, v162
	v_or_b32_e32 v7, 51, v2
	s_nop 0
	v_cndmask_b32_e32 v125, v184, v125, vcc
	v_cmp_le_i32_e32 vcc, v7, v162
	v_or_b32_e32 v7, 24, v2
	s_nop 0
	v_cndmask_b32_e32 v109, v184, v109, vcc
	v_cmp_le_i32_e32 vcc, v7, v162
	v_or_b32_e32 v7, 56, v2
	s_nop 0
	v_cndmask_b32_e32 v126, v184, v126, vcc
	v_cmp_le_i32_e32 vcc, v7, v162
	v_or_b32_e32 v7, 25, v2
	s_nop 0
	v_cndmask_b32_e32 v110, v184, v110, vcc
	v_cmp_le_i32_e32 vcc, v7, v162
	v_or_b32_e32 v7, 57, v2
	s_nop 0
	v_cndmask_b32_e32 v127, v184, v127, vcc
	v_cmp_le_i32_e32 vcc, v7, v162
	v_or_b32_e32 v7, 26, v2
	s_nop 0
	v_cndmask_b32_e32 v111, v184, v111, vcc
	v_cmp_le_i32_e32 vcc, v7, v162
	v_or_b32_e32 v7, 58, v2
	s_nop 0
	v_cndmask_b32_e32 v128, v184, v128, vcc
	v_cmp_le_i32_e32 vcc, v7, v162
	v_or_b32_e32 v7, 27, v2
	v_or_b32_e32 v2, 59, v2
	v_cndmask_b32_e32 v112, v184, v112, vcc
	v_cmp_le_i32_e32 vcc, v7, v162
	s_nop 1
	v_cndmask_b32_e32 v129, v184, v129, vcc
	v_cmp_le_i32_e32 vcc, v2, v162
	s_nop 1
	v_cndmask_b32_e32 v113, v184, v113, vcc

;     ...
;     for (int i = 0; i < nt; ++i) {
;         const int j = jn;
;         const bool more = (i + 1 < nt);
;         if (more) { jn = next(j); if (probe != 1) kv_gload<DV, HAS_V>(st, Kb, VTb, ldv, jn * 64); }
;         if (probe != 2) body(j, (const unsigned char*)(lds + (i & 1) * SB));
.Ldl_xdone:
	s_waitcnt lgkmcnt(0)
	s_barrier
	s_setprio 3
	s_cmp_le_i32 s64, s60
	s_cbranch_scc0 .Ldl_stage
	v_add3_u32 v199, s61, v168, v191
	s_add_i32 s65, s24, 1
	s_cmp_ge_u32 s65, s58
	s_cbranch_scc1 .Ldl_pvonly
	s_lshl_b32 s66, s65, 6
	s_cmp_le_i32 s66, s60
	s_cbranch_scc0 .Ldl_pvonly
	v_add3_u32 v7, s62, v191, v168

; #define MFMA(a, b, c) __builtin_amdgcn_mfma_f32_32x32x16_bf16((a), (b), (c), 0, 0, 0)
; DI void attn_scores(const unsigned char* kb, const bf16x8 (&qf)[4], int r, int h, f32x16& s0, f32x16& s1) {
; #pragma unroll
;     for (int i = 0; i < 16; ++i) { s0[i] = 0.f; s1[i] = 0.f; }
; #pragma unroll
;     for (int s = 0; s < 4; ++s) {
;         const bf16x8 k0 = *(const bf16x8*)(kb + r * KP + s * 32 + h * 16);
;         const bf16x8 k1 = *(const bf16x8*)(kb + (32 + r) * KP + s * 32 + h * 16);
;         s0 = MFMA(k0, qf[s], s0); s1 = MFMA(k1, qf[s], s1);
;     }
; }
; template <int DV>
; DI void attn_pv(const unsigned char* vb, const bf16x8 (&pf)[2][2], int r, int h, f32x16 (&o)[DV / 32]) {
; #pragma unroll
;     for (int dt = 0; dt < DV / 32; ++dt)
; #pragma unroll
;         for (int mt = 0; mt < 2; ++mt)
; #pragma unroll
;             for (int sp = 0; sp < 2; ++sp) {
;                 const bf16x8 vf = *(const bf16x8*)(vb + (dt * 32 + r) * VP + (2 * mt + sp) * 32 + h * 16);
;                 o[dt] = MFMA(vf, pf[mt][sp], o[dt]);
;             }
; }
	ds_read_b128 v[214:217], v199 offset:9216
	ds_read_b128 v[218:221], v199 offset:9248
	ds_read_b128 v[222:225], v199 offset:9280
	ds_read_b128 v[226:229], v199 offset:9312
	s_waitcnt lgkmcnt(3)
	v_mfma_f32_32x32x16_bf16 v[66:81], v[214:217], v[200:203], v[66:81]
	ds_read_b128 v[214:217], v199 offset:13824
	s_waitcnt lgkmcnt(3)
	v_mfma_f32_32x32x16_bf16 v[66:81], v[218:221], v[204:207], v[66:81]
	ds_read_b128 v[218:221], v199 offset:13856
	s_waitcnt lgkmcnt(3)
	v_mfma_f32_32x32x16_bf16 v[66:81], v[222:225], v[208:211], v[66:81]
	ds_read_b128 v[222:225], v199 offset:13888
	s_waitcnt lgkmcnt(3)
	v_mfma_f32_32x32x16_bf16 v[66:81], v[226:229], v[12:15], v[66:81]
	ds_read_b128 v[226:229], v199 offset:13920
	s_waitcnt lgkmcnt(3)
	v_mfma_f32_32x32x16_bf16 v[50:65], v[214:217], v[200:203], v[50:65]
	ds_read_b128 v[214:217], v199 offset:18432
	s_waitcnt lgkmcnt(3)
	v_mfma_f32_32x32x16_bf16 v[50:65], v[218:221], v[204:207], v[50:65]
	ds_read_b128 v[218:221], v199 offset:18464
	s_waitcnt lgkmcnt(3)
	v_mfma_f32_32x32x16_bf16 v[50:65], v[222:225], v[208:211], v[50:65]
	ds_read_b128 v[222:225], v199 offset:18496
	s_waitcnt lgkmcnt(3)
	v_mfma_f32_32x32x16_bf16 v[50:65], v[226:229], v[12:15], v[50:65]
	ds_read_b128 v[226:229], v199 offset:18528
	s_waitcnt lgkmcnt(3)
	v_mfma_f32_32x32x16_bf16 v[34:49], v[214:217], v[200:203], v[34:49]
	ds_read_b128 v[214:217], v199 offset:23040
	s_waitcnt lgkmcnt(3)
	v_mfma_f32_32x32x16_bf16 v[34:49], v[218:221], v[204:207], v[34:49]
	ds_read_b128 v[218:221], v199 offset:23072
	s_waitcnt lgkmcnt(3)
	v_mfma_f32_32x32x16_bf16 v[34:49], v[222:225], v[208:211], v[34:49]
	ds_read_b128 v[222:225], v199 offset:23104
	s_waitcnt lgkmcnt(3)
	v_mfma_f32_32x32x16_bf16 v[34:49], v[226:229], v[12:15], v[34:49]
	ds_read_b128 v[226:229], v199 offset:23136
	s_waitcnt lgkmcnt(3)
	v_mfma_f32_32x32x16_bf16 v[18:33], v[214:217], v[200:203], v[18:33]
	ds_read_b128 v[214:217], v7 offset:0
	s_waitcnt lgkmcnt(3)
	v_mfma_f32_32x32x16_bf16 v[18:33], v[218:221], v[204:207], v[18:33]
	ds_read_b128 v[218:221], v7 offset:4608
	s_waitcnt lgkmcnt(3)
	v_mfma_f32_32x32x16_bf16 v[18:33], v[222:225], v[208:211], v[18:33]
	ds_read_b128 v[222:225], v7 offset:32
	s_waitcnt lgkmcnt(3)
	v_mfma_f32_32x32x16_bf16 v[18:33], v[226:229], v[12:15], v[18:33]
	ds_read_b128 v[226:229], v7 offset:4640
	s_waitcnt lgkmcnt(3)
	v_mfma_f32_32x32x16_bf16 v[114:129], v[214:217], v[130:133], 0
	ds_read_b128 v[214:217], v7 offset:64
	s_waitcnt lgkmcnt(3)
	v_mfma_f32_32x32x16_bf16 v[98:113], v[218:221], v[130:133], 0
	ds_read_b128 v[218:221], v7 offset:4672
	s_waitcnt lgkmcnt(3)
	v_mfma_f32_32x32x16_bf16 v[114:129], v[222:225], v[134:137], v[114:129]
	ds_read_b128 v[222:225], v7 offset:96
	s_waitcnt lgkmcnt(3)
	v_mfma_f32_32x32x16_bf16 v[98:113], v[226:229], v[134:137], v[98:113]
	ds_read_b128 v[226:229], v7 offset:4704
	s_waitcnt lgkmcnt(3)
	v_mfma_f32_32x32x16_bf16 v[114:129], v[214:217], v[138:141], v[114:129]
	s_waitcnt lgkmcnt(2)
	v_mfma_f32_32x32x16_bf16 v[98:113], v[218:221], v[138:141], v[98:113]
	s_waitcnt lgkmcnt(1)
	v_mfma_f32_32x32x16_bf16 v[114:129], v[222:225], v[142:145], v[114:129]
	s_waitcnt lgkmcnt(0)
	v_mfma_f32_32x32x16_bf16 v[98:113], v[226:229], v[142:145], v[98:113]
	s_branch .Ldl_stage

; DI int crow(int i, int h) { return (i & 3) + 8 * (i >> 2) + 4 * h; }
; #define NEG_INF (-__builtin_inff())
;     ...
;             const bool mine = (mysel >> j) & 1ull;
;             if (__ballot(mine) != 0ull) {
;                 f32x16 s0, s1; attn_scores(sb, qf, r, h, s0, s1);
;                 if (j == (qb >> 6)) {
;                     const int lim = mine ? (qpos - 64 * j) : -1;
; #pragma unroll
;                     for (int i = 0; i < 16; ++i) {
;                         const int kl = crow(i, h);
;                         if (kl > lim) s0[i] = NEG_INF;
;                         if (kl + 32 > lim) s1[i] = NEG_INF;
.Lns_loop:
	s_setprio 0
	s_cmp_eq_u64 s[14:15], 0
	s_cbranch_scc1 .Lns_xdone
	s_nop 3
	s_cmp_lg_u32 s12, s21
	s_cbranch_scc1 .Lns_nomask
	v_cndmask_b32_e64 v168, -1, v206, s[14:15]
	v_sub_u32_e32 v168, v168, v181

; DI int crow(int i, int h) { return (i & 3) + 8 * (i >> 2) + 4 * h; }
; #define NEG_INF (-__builtin_inff())
;     ...
;                 if (j == (qb >> 6)) {
;                     const int lim = mine ? (qpos - 64 * j) : -1;
; #pragma unroll
;                     for (int i = 0; i < 16; ++i) {
;                         const int kl = crow(i, h);
;                         if (kl > lim) s0[i] = NEG_INF;
;                         if (kl + 32 > lim) s1[i] = NEG_INF;
;                     }
	v_cmp_le_i32_e32 vcc, 0, v168
	s_nop 1
	v_cndmask_b32_e32 v98, v200, v98, vcc
	v_cmp_le_i32_e32 vcc, 32, v168
	s_nop 1
	v_cndmask_b32_e32 v82, v200, v82, vcc
	v_cmp_le_i32_e32 vcc, 1, v168
	s_nop 1
	v_cndmask_b32_e32 v99, v200, v99, vcc
	v_cmp_le_i32_e32 vcc, 33, v168
	s_nop 1
	v_cndmask_b32_e32 v83, v200, v83, vcc
	v_cmp_le_i32_e32 vcc, 2, v168
	s_nop 1
	v_cndmask_b32_e32 v100, v200, v100, vcc
	v_cmp_le_i32_e32 vcc, 34, v168
	s_nop 1
	v_cndmask_b32_e32 v84, v200, v84, vcc
	v_cmp_le_i32_e32 vcc, 3, v168
	s_nop 1
	v_cndmask_b32_e32 v101, v200, v101, vcc
	v_cmp_le_i32_e32 vcc, 35, v168
	s_nop 1
	v_cndmask_b32_e32 v85, v200, v85, vcc
	v_cmp_le_i32_e32 vcc, 8, v168
	s_nop 1
	v_cndmask_b32_e32 v102, v200, v102, vcc
	v_cmp_le_i32_e32 vcc, 40, v168
	s_nop 1
	v_cndmask_b32_e32 v86, v200, v86, vcc
	v_cmp_le_i32_e32 vcc, 9, v168
	s_nop 1
	v_cndmask_b32_e32 v103, v200, v103, vcc
	v_cmp_le_i32_e32 vcc, 41, v168
	s_nop 1
	v_cndmask_b32_e32 v87, v200, v87, vcc
	v_cmp_le_i32_e32 vcc, 10, v168
	s_nop 1
	v_cndmask_b32_e32 v104, v200, v104, vcc
	v_cmp_le_i32_e32 vcc, 42, v168
	s_nop 1
	v_cndmask_b32_e32 v88, v200, v88, vcc
	v_cmp_le_i32_e32 vcc, 11, v168
	s_nop 1
	v_cndmask_b32_e32 v105, v200, v105, vcc
	v_cmp_le_i32_e32 vcc, 43, v168
	s_nop 1
	v_cndmask_b32_e32 v89, v200, v89, vcc
	v_cmp_le_i32_e32 vcc, 16, v168
	s_nop 1
	v_cndmask_b32_e32 v106, v200, v106, vcc
	v_cmp_le_i32_e32 vcc, 48, v168
	s_nop 1
	v_cndmask_b32_e32 v90, v200, v90, vcc
	v_cmp_le_i32_e32 vcc, 17, v168
	s_nop 1
	v_cndmask_b32_e32 v107, v200, v107, vcc
	v_cmp_le_i32_e32 vcc, 49, v168
	s_nop 1
	v_cndmask_b32_e32 v91, v200, v91, vcc
	v_cmp_le_i32_e32 vcc, 18, v168
	s_nop 1
	v_cndmask_b32_e32 v108, v200, v108, vcc
	v_cmp_le_i32_e32 vcc, 50, v168
	s_nop 1
	v_cndmask_b32_e32 v92, v200, v92, vcc
	v_cmp_le_i32_e32 vcc, 19, v168
	s_nop 1
	v_cndmask_b32_e32 v109, v200, v109, vcc
	v_cmp_le_i32_e32 vcc, 51, v168
	s_nop 1
	v_cndmask_b32_e32 v93, v200, v93, vcc
	v_cmp_le_i32_e32 vcc, 24, v168
	s_nop 1
	v_cndmask_b32_e32 v110, v200, v110, vcc
	v_cmp_le_i32_e32 vcc, 56, v168
	s_nop 1
	v_cndmask_b32_e32 v94, v200, v94, vcc
	v_cmp_le_i32_e32 vcc, 25, v168
	s_nop 1
	v_cndmask_b32_e32 v111, v200, v111, vcc
	v_cmp_le_i32_e32 vcc, 57, v168
	s_nop 1
	v_cndmask_b32_e32 v95, v200, v95, vcc
	v_cmp_le_i32_e32 vcc, 26, v168
	s_nop 1
	v_cndmask_b32_e32 v112, v200, v112, vcc
	v_cmp_le_i32_e32 vcc, 58, v168
	s_nop 1
	v_cndmask_b32_e32 v96, v200, v96, vcc
	v_cmp_le_i32_e32 vcc, 27, v168
	s_nop 1
	v_cndmask_b32_e32 v113, v200, v113, vcc
	v_cmp_le_i32_e32 vcc, 59, v168
	s_nop 1
	v_cndmask_b32_e32 v97, v200, v97, vcc

;     ...
;     for (int i = 0; i < nt; ++i) {
;         const int j = jn;
;         const bool more = (i + 1 < nt);
;         if (more) { jn = next(j); if (probe != 1) kv_gload<DV, HAS_V>(st, Kb, VTb, ldv, jn * 64); }
;         if (probe != 2) body(j, (const unsigned char*)(lds + (i & 1) * SB));
.Lns_xdone:
	s_waitcnt lgkmcnt(0)
	s_barrier
	s_setprio 3
	s_add_i32 s26, s13, 1
	s_mov_b64 s[16:17], 0
	s_cmp_ge_u32 s26, s2
	s_cbranch_scc1 .Lns_y1

;     ...
;             const bool mine = (mysel >> j) & 1ull;
	v_lshrrev_b64 v[168:169], s8, v[124:125]
	v_and_b32_e32 v168, 1, v168
	v_cmp_ne_u32_e64 s[16:17], 0, v168


;     ...
;         kv_loop<64, true>(lds, Kw, VwT, 4096, thi - tlo + 1, tlo, inc, [&](int j, const unsigned char* sb) {
;             const int k0 = j * 64;
;             if (k0 > qb + 31 || k0 + 63 <= qb - 512) return;
;             f32x16 s0, s1; attn_scores(sb, qf, r, h, s0, s1);
;             if (!(k0 + 63 <= qb && k0 > qb + 31 - 512)) {
.Lnw_loop:
	s_setprio 0
	s_cmp_eq_u32 s16, 0
	s_cbranch_scc1 .Lnw_xdone
	s_nop 3
	s_lshl_b32 s6, s14, 6
	s_add_i32 s7, s6, 63
	s_cmp_gt_i32 s7, s21
	s_cbranch_scc1 .Lnw_mask
	s_add_i32 s7, s21, 0xfffffe1f
	s_cmp_le_i32 s6, s7
	s_cbranch_scc0 .Lnw_nomask

;     ...
;     for (int i = 0; i < nt; ++i) {
;         const int j = jn;
;         const bool more = (i + 1 < nt);
;         if (more) { jn = next(j); if (probe != 1) kv_gload<DV, HAS_V>(st, Kb, VTb, ldv, jn * 64); }
;         if (probe != 2) body(j, (const unsigned char*)(lds + (i & 1) * SB));
.Lnw_xdone:
	s_waitcnt lgkmcnt(0)
	s_barrier
	s_setprio 3
	s_add_i32 s26, s13, 1
	s_mov_b32 s17, 0
	s_cmp_ge_u32 s26, s12
	s_cbranch_scc1 .Lnw_y1
	s_add_i32 s15, s14, 1

;     ...
;             const int k0 = j * 64;
;             if (k0 > qb + 31 || k0 + 63 <= qb - 512) return;
	s_lshl_b32 s6, s15, 6
	s_add_i32 s7, s21, 31
	s_cmp_le_i32 s6, s7
	s_cselect_b32 s17, 1, 0
	s_add_i32 s6, s6, 63
	s_add_i32 s7, s21, 0xfffffe00
	s_cmp_gt_i32 s6, s7
	s_cselect_b32 s7, 1, 0
	s_and_b32 s17, s17, s7

